# combo8
# speedup vs baseline: 1.0081x; 1.0030x over previous
.LBB0_249:
	s_ashr_i32 s21, s20, 31
	s_lshl_b64 s[4:5], s[20:21], 18
	s_add_u32 s22, s45, s4
	s_addc_u32 s23, s76, s5
	s_ashr_i32 s19, s18, 31
	s_lshl_b64 s[26:27], s[18:19], 18
	v_readlane_b32 s8, v253, 30
	v_readlane_b32 s9, v253, 31
	s_add_u32 s24, s8, s26
	s_addc_u32 s25, s9, s27
	s_ashr_i32 s13, s12, 31
	s_lshl_b64 s[4:5], s[12:13], 18
	s_add_u32 s6, s45, s4
	s_addc_u32 s7, s76, s5
	s_ashr_i32 s15, s14, 31
	s_lshl_b64 s[4:5], s[14:15], 18
	s_add_u32 s8, s8, s4
	s_addc_u32 s9, s9, s5
	s_and_b64 s[4:5], s[16:17], exec
	s_cselect_b32 s15, s7, s23
	s_cselect_b32 s19, s6, s22
	s_cselect_b32 s21, s9, s25
	s_cselect_b32 s78, s8, s24
	s_lshl_b32 s13, s18, 7
	s_sub_i32 s4, s20, 35
	s_cmp_gt_u32 s4, 7
	s_mov_b64 s[4:5], -1
	s_cbranch_scc0 .LBB0_789
	v_mov_b32_e32 v98, v180
	s_mov_b32 s4, 0x1ffffc0
	v_lshlrev_b32_e32 v0, 3, v98
	s_waitcnt vmcnt(23)
	v_ashrrev_i32_e32 v5, 3, v98
	v_and_b32_e32 v0, 56, v0
	v_lshl_or_b32 v0, v5, 10, v0
	v_and_b32_e32 v2, 15, v98
	v_lshrrev_b32_e32 v3, 4, v98
	s_waitcnt vmcnt(22)
	v_lshrrev_b32_e32 v6, 1, v98
	v_bfe_u32 v7, v98, 1, 3
	v_lshlrev_b64 v[168:169], 1, v[0:1]
	v_xor_b32_e32 v8, v3, v98
	v_bitop3_b32 v99, v3, v7, 3 bitop3:0x6c
	v_and_or_b32 v101, v6, s4, v2
	v_lshl_add_u64 v[2:3], s[22:23], 0, v[168:169]
	v_bfe_u32 v4, v98, 4, 2
	s_waitcnt vmcnt(21)
	v_add_co_u32_e32 v10, vcc, s71, v2
	v_bitop3_b32 v100, v4, v7, 4 bitop3:0x36
	v_lshl_add_u64 v[6:7], s[24:25], 0, v[168:169]
	v_addc_co_u32_e32 v11, vcc, 0, v3, vcc
	s_waitcnt vmcnt(20)
	v_add_co_u32_e32 v14, vcc, s71, v6
	v_lshlrev_b32_e32 v0, 4, v8
	s_nop 0
	v_addc_co_u32_e32 v15, vcc, 0, v7, vcc
	s_waitcnt vmcnt(19)
	v_add_co_u32_e32 v18, vcc, s0, v2
	v_and_b32_e32 v0, 0x70, v0
	s_nop 0
	v_addc_co_u32_e32 v19, vcc, 0, v3, vcc
	s_waitcnt vmcnt(18)
	v_add_co_u32_e32 v22, vcc, s0, v6
	v_lshl_or_b32 v167, v5, 7, v0
	s_nop 0
	v_addc_co_u32_e32 v23, vcc, 0, v7, vcc
	s_waitcnt vmcnt(17)
	v_add_co_u32_e32 v26, vcc, s1, v2
	s_waitcnt vmcnt(7)
	ds_write_b128 v167, v[34:37]
	s_waitcnt vmcnt(6)
	ds_write_b128 v167, v[38:41] offset:16384
	s_waitcnt vmcnt(5)
	ds_write_b128 v167, v[42:45] offset:4096
	s_waitcnt vmcnt(4)
	ds_write_b128 v167, v[46:49] offset:20480
	s_waitcnt vmcnt(3)
	ds_write_b128 v167, v[50:53] offset:8192
	s_waitcnt vmcnt(2)
	ds_write_b128 v167, v[54:57] offset:24576
	s_waitcnt vmcnt(1)
	ds_write_b128 v167, v[58:61] offset:12288
	s_waitcnt vmcnt(0)
	ds_write_b128 v167, v[62:65] offset:28672
	v_addc_co_u32_e32 v27, vcc, 0, v3, vcc
	v_add_co_u32_e32 v30, vcc, s1, v6
	v_lshlrev_b32_e32 v98, 7, v98
	s_nop 0
	v_addc_co_u32_e32 v31, vcc, 0, v7, vcc
	global_load_dwordx4 v[66:69], v[2:3], off offset:128
	s_nop 0
	global_load_dwordx4 v[2:5], v[2:3], off offset:256
	s_nop 0
	global_load_dwordx4 v[70:73], v[6:7], off offset:128
	s_nop 0
	global_load_dwordx4 v[6:9], v[6:7], off offset:256
	s_nop 0
	global_load_dwordx4 v[74:77], v[10:11], off offset:128
	s_nop 0
	global_load_dwordx4 v[10:13], v[10:11], off offset:256
	s_nop 0
	global_load_dwordx4 v[78:81], v[14:15], off offset:128
	s_nop 0
	global_load_dwordx4 v[14:17], v[14:15], off offset:256
	s_nop 0
	global_load_dwordx4 v[82:85], v[18:19], off offset:128
	s_nop 0
	global_load_dwordx4 v[18:21], v[18:19], off offset:256
	s_nop 0
	global_load_dwordx4 v[86:89], v[22:23], off offset:128
	s_nop 0
	global_load_dwordx4 v[22:25], v[22:23], off offset:256
	s_nop 0
	global_load_dwordx4 v[90:93], v[26:27], off offset:128
	s_nop 0
	global_load_dwordx4 v[26:29], v[26:27], off offset:256
	s_nop 0
	global_load_dwordx4 v[94:97], v[30:31], off offset:128
	s_nop 0
	global_load_dwordx4 v[30:33], v[30:31], off offset:256
	v_lshlrev_b32_e32 v0, 7, v101
	v_lshlrev_b32_e32 v99, 4, v99
	v_and_b32_e32 v98, 0x2780, v98
	v_or_b32_e32 v165, v0, v99
	v_or_b32_e32 v170, v98, v99
	v_lshlrev_b32_e32 v99, 4, v100
	s_add_u32 s6, s68, s26
	v_mov_b32_e32 v150, 0
	s_mov_b32 s10, 0
	v_or_b32_e32 v0, v0, v99
	v_or_b32_e32 v163, v98, v99
	s_addc_u32 s7, s69, s27
	s_movk_i32 s11, 0x100
	s_mov_b64 s[8:9], s[22:23]
	v_mov_b32_e32 v151, v150
	v_mov_b32_e32 v152, v150
	v_mov_b32_e32 v153, v150
	v_mov_b32_e32 v154, v150
	v_mov_b32_e32 v155, v150
	v_mov_b32_e32 v156, v150
	v_mov_b32_e32 v157, v150
	v_mov_b32_e32 v158, v150
	v_mov_b32_e32 v159, v150
	v_mov_b32_e32 v160, v150
	v_mov_b32_e32 v161, v150
	v_mov_b32_e32 v98, v150
	v_mov_b32_e32 v99, v150
	v_mov_b32_e32 v100, v150
	v_mov_b32_e32 v101, v150
	v_mov_b32_e32 v130, v150
	v_mov_b32_e32 v131, v150
	v_mov_b32_e32 v132, v150
	v_mov_b32_e32 v133, v150
	v_mov_b32_e32 v134, v150
	v_mov_b32_e32 v135, v150
	v_mov_b32_e32 v136, v150
	v_mov_b32_e32 v137, v150
	v_mov_b32_e32 v122, v150
	v_mov_b32_e32 v123, v150
	v_mov_b32_e32 v124, v150
	v_mov_b32_e32 v125, v150
	v_mov_b32_e32 v110, v150
	v_mov_b32_e32 v111, v150
	v_mov_b32_e32 v112, v150
	v_mov_b32_e32 v113, v150
	v_mov_b32_e32 v114, v150
	v_mov_b32_e32 v115, v150
	v_mov_b32_e32 v116, v150
	v_mov_b32_e32 v117, v150
	v_mov_b32_e32 v106, v150
	v_mov_b32_e32 v107, v150
	v_mov_b32_e32 v108, v150
	v_mov_b32_e32 v109, v150
	v_mov_b32_e32 v102, v150
	v_mov_b32_e32 v103, v150
	v_mov_b32_e32 v104, v150
	v_mov_b32_e32 v105, v150
	v_mov_b32_e32 v118, v150
	v_mov_b32_e32 v119, v150
	v_mov_b32_e32 v120, v150
	v_mov_b32_e32 v121, v150
	v_mov_b32_e32 v138, v150
	v_mov_b32_e32 v139, v150
	v_mov_b32_e32 v140, v150
	v_mov_b32_e32 v141, v150
	v_mov_b32_e32 v142, v150
	v_mov_b32_e32 v143, v150
	v_mov_b32_e32 v144, v150
	v_mov_b32_e32 v145, v150
	v_mov_b32_e32 v146, v150
	v_mov_b32_e32 v147, v150
	v_mov_b32_e32 v148, v150
	v_mov_b32_e32 v149, v150
	v_mov_b32_e32 v126, v150
	v_mov_b32_e32 v127, v150
	v_mov_b32_e32 v128, v150
	v_mov_b32_e32 v129, v150
	s_mov_b32 s31, 0x1cb24000
	s_mov_b32 s34, 0x1cb34000
	s_mov_b32 s35, 0x1cb44000
	s_mov_b32 s36, 0x1cb54000
	s_waitcnt lgkmcnt(0)
	s_barrier
	v_add_u32_e32 v234, 0x10000, v168
	v_add_u32_e32 v235, 0x20000, v168
	v_add_u32_e32 v248, 0x30000, v168
	ds_read_b128 v[236:239], v165
	ds_read_b128 v[240:243], v170 offset:16384
	ds_read_b128 v[198:201], v165 offset:2048
	ds_read_b128 v[244:247], v170 offset:18432
	ds_read_b128 v[206:209], v170 offset:20480
	ds_read_b128 v[210:213], v170 offset:22528
	ds_read_b128 v[188:191], v165 offset:4096
	ds_read_b128 v[192:195], v165 offset:6144
.LBB0_251:
	s_cmp_lt_u32 s10, 12
	s_waitcnt lgkmcnt(6)
	v_mfma_f32_16x16x32_bf16 v[126:129], v[236:239], v[240:243], v[126:129]
	s_cselect_b64 s[4:5], -1, 0
	s_waitcnt lgkmcnt(4)
	v_mfma_f32_16x16x32_bf16 v[146:149], v[236:239], v[244:247], v[146:149]
	s_waitcnt lgkmcnt(3)
	v_mfma_f32_16x16x32_bf16 v[142:145], v[236:239], v[206:209], v[142:145]
	s_waitcnt lgkmcnt(2)
	v_mfma_f32_16x16x32_bf16 v[138:141], v[236:239], v[210:213], v[138:141]
	v_mfma_f32_16x16x32_bf16 v[118:121], v[198:201], v[240:243], v[118:121]
	v_mfma_f32_16x16x32_bf16 v[102:105], v[198:201], v[244:247], v[102:105]
	v_mfma_f32_16x16x32_bf16 v[106:109], v[198:201], v[206:209], v[106:109]
	v_mfma_f32_16x16x32_bf16 v[114:117], v[198:201], v[210:213], v[114:117]
	s_waitcnt lgkmcnt(1)
	v_mfma_f32_16x16x32_bf16 v[110:113], v[188:191], v[240:243], v[110:113]
	v_mfma_f32_16x16x32_bf16 v[122:125], v[188:191], v[244:247], v[122:125]
	v_mfma_f32_16x16x32_bf16 v[134:137], v[188:191], v[206:209], v[134:137]
	v_mfma_f32_16x16x32_bf16 v[130:133], v[188:191], v[210:213], v[130:133]
	s_waitcnt lgkmcnt(0)
	v_mfma_f32_16x16x32_bf16 v[98:101], v[192:195], v[240:243], v[98:101]
	v_mfma_f32_16x16x32_bf16 v[158:161], v[192:195], v[244:247], v[158:161]
	ds_read_b128 v[172:175], v163 offset:16384
	ds_read_b128 v[176:179], v0
	ds_read_b128 v[202:205], v0 offset:2048
	v_mfma_f32_16x16x32_bf16 v[154:157], v[192:195], v[206:209], v[154:157]
	ds_read_b128 v[206:209], v163 offset:18432
	ds_read_b128 v[214:217], v0 offset:4096
	ds_read_b128 v[218:221], v0 offset:6144
	v_mfma_f32_16x16x32_bf16 v[150:153], v[192:195], v[210:213], v[150:153]
	ds_read_b128 v[198:201], v163 offset:20480
	ds_read_b128 v[210:213], v163 offset:22528
	s_waitcnt vmcnt(15)
	ds_write_b128 v167, v[66:69] offset:32768
	s_waitcnt vmcnt(13)
	ds_write_b128 v167, v[70:73] offset:49152
	s_waitcnt vmcnt(11)
	ds_write_b128 v167, v[74:77] offset:36864
	s_waitcnt vmcnt(9)
	ds_write_b128 v167, v[78:81] offset:53248
	s_waitcnt vmcnt(7)
	ds_write_b128 v167, v[82:85] offset:40960
	s_waitcnt vmcnt(5)
	ds_write_b128 v167, v[86:89] offset:57344
	s_waitcnt vmcnt(3)
	ds_write_b128 v167, v[90:93] offset:45056
	s_waitcnt vmcnt(1)
	ds_write_b128 v167, v[94:97] offset:61440
	s_waitcnt lgkmcnt(14)
	v_mfma_f32_16x16x32_bf16 v[126:129], v[176:179], v[172:175], v[126:129]
	s_add_u32 s98, s6, s31
	s_addc_u32 s99, s7, 0
	global_load_dwordx4 v[66:69], v168, s[8:9] offset:384
	s_waitcnt lgkmcnt(13)
	v_mfma_f32_16x16x32_bf16 v[118:121], v[202:205], v[172:175], v[118:121]
	s_waitcnt lgkmcnt(11)
	v_mfma_f32_16x16x32_bf16 v[110:113], v[214:217], v[172:175], v[110:113]
	global_load_dwordx4 v[70:73], v168, s[98:99] offset:384
	global_load_dwordx4 v[74:77], v234, s[8:9] offset:384
	global_load_dwordx4 v[78:81], v234, s[98:99] offset:384
	global_load_dwordx4 v[82:85], v235, s[8:9] offset:384
	s_waitcnt lgkmcnt(10)
	v_mfma_f32_16x16x32_bf16 v[98:101], v[218:221], v[172:175], v[98:101]
	global_load_dwordx4 v[86:89], v235, s[98:99] offset:384
	global_load_dwordx4 v[90:93], v248, s[8:9] offset:384
	global_load_dwordx4 v[94:97], v248, s[98:99] offset:384
	s_waitcnt lgkmcnt(0)
	s_barrier
	ds_read_b128 v[172:175], v165 offset:32768
	v_mfma_f32_16x16x32_bf16 v[146:149], v[176:179], v[206:209], v[146:149]
	s_and_b64 vcc, s[4:5], exec
	s_cselect_b32 s5, s23, s15
	s_cselect_b32 s4, s22, s19
	v_mfma_f32_16x16x32_bf16 v[142:145], v[176:179], v[198:201], v[142:145]
	s_cselect_b32 s29, s25, s21
	s_cselect_b32 s28, s24, s78
	s_and_b32 s30, s11, 0x380
	v_mfma_f32_16x16x32_bf16 v[138:141], v[176:179], v[210:213], v[138:141]
	s_lshl_b32 s64, s30, 1
	s_add_i32 s10, s10, 2
	s_add_u32 s6, s6, 0x100
	v_mfma_f32_16x16x32_bf16 v[102:105], v[202:205], v[206:209], v[102:105]
	s_addc_u32 s7, s7, 0
	s_add_u32 s8, s8, 0x100
	s_addc_u32 s9, s9, 0
	v_mfma_f32_16x16x32_bf16 v[106:109], v[202:205], v[198:201], v[106:109]
	s_addk_i32 s11, 0x80
	v_mfma_f32_16x16x32_bf16 v[114:117], v[202:205], v[210:213], v[114:117]
	v_mfma_f32_16x16x32_bf16 v[122:125], v[214:217], v[206:209], v[122:125]
	v_mfma_f32_16x16x32_bf16 v[134:137], v[214:217], v[198:201], v[134:137]
	v_mfma_f32_16x16x32_bf16 v[130:133], v[214:217], v[210:213], v[130:133]
	v_mfma_f32_16x16x32_bf16 v[158:161], v[218:221], v[206:209], v[158:161]
	v_mfma_f32_16x16x32_bf16 v[154:157], v[218:221], v[198:201], v[154:157]
	ds_read_b128 v[176:179], v170 offset:49152
	ds_read_b128 v[198:201], v165 offset:34816
	ds_read_b128 v[202:205], v170 offset:51200
	v_mfma_f32_16x16x32_bf16 v[150:153], v[218:221], v[210:213], v[150:153]
	ds_read_b128 v[206:209], v170 offset:53248
	ds_read_b128 v[210:213], v170 offset:55296
	ds_read_b128 v[188:191], v165 offset:36864
	ds_read_b128 v[192:195], v165 offset:38912
	s_waitcnt lgkmcnt(6)
	v_mfma_f32_16x16x32_bf16 v[126:129], v[172:175], v[176:179], v[126:129]
	s_waitcnt lgkmcnt(4)
	v_mfma_f32_16x16x32_bf16 v[146:149], v[172:175], v[202:205], v[146:149]
	s_waitcnt lgkmcnt(3)
	v_mfma_f32_16x16x32_bf16 v[142:145], v[172:175], v[206:209], v[142:145]
	s_waitcnt lgkmcnt(2)
	v_mfma_f32_16x16x32_bf16 v[138:141], v[172:175], v[210:213], v[138:141]
	v_mfma_f32_16x16x32_bf16 v[118:121], v[198:201], v[176:179], v[118:121]
	v_mfma_f32_16x16x32_bf16 v[102:105], v[198:201], v[202:205], v[102:105]
	v_mfma_f32_16x16x32_bf16 v[106:109], v[198:201], v[206:209], v[106:109]
	v_mfma_f32_16x16x32_bf16 v[114:117], v[198:201], v[210:213], v[114:117]
	ds_read_b128 v[214:217], v0 offset:32768
	s_waitcnt lgkmcnt(2)
	v_mfma_f32_16x16x32_bf16 v[110:113], v[188:191], v[176:179], v[110:113]
	v_mfma_f32_16x16x32_bf16 v[122:125], v[188:191], v[202:205], v[122:125]
	v_mfma_f32_16x16x32_bf16 v[134:137], v[188:191], v[206:209], v[134:137]
	v_mfma_f32_16x16x32_bf16 v[130:133], v[188:191], v[210:213], v[130:133]
	ds_read_b128 v[172:175], v0 offset:34816
	ds_read_b128 v[218:221], v163 offset:49152
	ds_read_b128 v[222:225], v163 offset:51200
	s_waitcnt lgkmcnt(4)
	v_mfma_f32_16x16x32_bf16 v[98:101], v[192:195], v[176:179], v[98:101]
	ds_read_b128 v[176:179], v163 offset:53248
	ds_read_b128 v[226:229], v0 offset:36864
	ds_read_b128 v[230:233], v0 offset:38912
	v_mfma_f32_16x16x32_bf16 v[158:161], v[192:195], v[202:205], v[158:161]
	ds_read_b128 v[202:205], v163 offset:55296
	ds_write_b128 v167, v[2:5]
	ds_write_b128 v167, v[6:9] offset:16384
	ds_write_b128 v167, v[10:13] offset:4096
	ds_write_b128 v167, v[14:17] offset:20480
	ds_write_b128 v167, v[18:21] offset:8192
	ds_write_b128 v167, v[22:25] offset:24576
	ds_write_b128 v167, v[26:29] offset:12288
	s_waitcnt vmcnt(8)
	ds_write_b128 v167, v[30:33] offset:28672
	s_add_u32 s100, s4, s64
	s_addc_u32 s101, s5, 0
	s_add_u32 s98, s28, s64
	s_addc_u32 s99, s29, 0
	global_load_dwordx4 v[2:5], v168, s[100:101]
	global_load_dwordx4 v[6:9], v168, s[98:99]
	v_mfma_f32_16x16x32_bf16 v[154:157], v[192:195], v[206:209], v[154:157]
	v_mfma_f32_16x16x32_bf16 v[150:153], v[192:195], v[210:213], v[150:153]
	global_load_dwordx4 v[10:13], v234, s[100:101]
	global_load_dwordx4 v[14:17], v234, s[98:99]
	global_load_dwordx4 v[18:21], v235, s[100:101]
	global_load_dwordx4 v[22:25], v235, s[98:99]
	global_load_dwordx4 v[26:29], v248, s[100:101]
	s_waitcnt lgkmcnt(13)
	v_mfma_f32_16x16x32_bf16 v[126:129], v[214:217], v[218:221], v[126:129]
	global_load_dwordx4 v[30:33], v248, s[98:99]
	s_waitcnt lgkmcnt(0)
	s_barrier
	ds_read_b128 v[236:239], v165
	ds_read_b128 v[240:243], v170 offset:16384
	ds_read_b128 v[198:201], v165 offset:2048
	ds_read_b128 v[244:247], v170 offset:18432
	ds_read_b128 v[206:209], v170 offset:20480
	ds_read_b128 v[210:213], v170 offset:22528
	ds_read_b128 v[188:191], v165 offset:4096
	ds_read_b128 v[192:195], v165 offset:6144
	v_mfma_f32_16x16x32_bf16 v[146:149], v[214:217], v[222:225], v[146:149]
	v_mfma_f32_16x16x32_bf16 v[142:145], v[214:217], v[176:179], v[142:145]
	v_mfma_f32_16x16x32_bf16 v[138:141], v[214:217], v[202:205], v[138:141]
	v_mfma_f32_16x16x32_bf16 v[118:121], v[172:175], v[218:221], v[118:121]
	v_mfma_f32_16x16x32_bf16 v[102:105], v[172:175], v[222:225], v[102:105]
	v_mfma_f32_16x16x32_bf16 v[106:109], v[172:175], v[176:179], v[106:109]
	v_mfma_f32_16x16x32_bf16 v[114:117], v[172:175], v[202:205], v[114:117]
	v_mfma_f32_16x16x32_bf16 v[110:113], v[226:229], v[218:221], v[110:113]
	v_mfma_f32_16x16x32_bf16 v[122:125], v[226:229], v[222:225], v[122:125]
	v_mfma_f32_16x16x32_bf16 v[134:137], v[226:229], v[176:179], v[134:137]
	v_mfma_f32_16x16x32_bf16 v[130:133], v[226:229], v[202:205], v[130:133]
	v_mfma_f32_16x16x32_bf16 v[98:101], v[230:233], v[218:221], v[98:101]
	v_mfma_f32_16x16x32_bf16 v[158:161], v[230:233], v[222:225], v[158:161]
	v_mfma_f32_16x16x32_bf16 v[154:157], v[230:233], v[176:179], v[154:157]
	v_mfma_f32_16x16x32_bf16 v[150:153], v[230:233], v[202:205], v[150:153]
	s_cbranch_vccnz .LBB0_251
	ds_read_b128 v[172:175], v165
	ds_read_b128 v[176:179], v170 offset:16384
	ds_read_b128 v[198:201], v170 offset:18432
	ds_read_b128 v[202:205], v170 offset:20480
	ds_read_b128 v[206:209], v170 offset:22528
	s_cmp_lt_i32 s20, 8
	s_waitcnt lgkmcnt(3)
	v_mfma_f32_16x16x32_bf16 v[126:129], v[172:175], v[176:179], v[126:129]
	s_cselect_b64 s[4:5], -1, 0
	s_and_b64 vcc, exec, s[4:5]
	s_waitcnt lgkmcnt(2)
	v_mfma_f32_16x16x32_bf16 v[146:149], v[172:175], v[198:201], v[146:149]
	s_waitcnt lgkmcnt(1)
	v_mfma_f32_16x16x32_bf16 v[142:145], v[172:175], v[202:205], v[142:145]
	s_waitcnt lgkmcnt(0)
	v_mfma_f32_16x16x32_bf16 v[138:141], v[172:175], v[206:209], v[138:141]
	ds_read_b128 v[172:175], v165 offset:2048
	s_waitcnt lgkmcnt(0)
	v_mfma_f32_16x16x32_bf16 v[118:121], v[172:175], v[176:179], v[118:121]
	v_mfma_f32_16x16x32_bf16 v[102:105], v[172:175], v[198:201], v[102:105]
	v_mfma_f32_16x16x32_bf16 v[106:109], v[172:175], v[202:205], v[106:109]
	v_mfma_f32_16x16x32_bf16 v[114:117], v[172:175], v[206:209], v[114:117]
	ds_read_b128 v[172:175], v165 offset:4096
	s_waitcnt lgkmcnt(0)
	v_mfma_f32_16x16x32_bf16 v[110:113], v[172:175], v[176:179], v[110:113]
	v_mfma_f32_16x16x32_bf16 v[122:125], v[172:175], v[198:201], v[122:125]
	v_mfma_f32_16x16x32_bf16 v[134:137], v[172:175], v[202:205], v[134:137]
	v_mfma_f32_16x16x32_bf16 v[130:133], v[172:175], v[206:209], v[130:133]
	ds_read_b128 v[172:175], v165 offset:6144
	s_waitcnt lgkmcnt(0)
	v_mfma_f32_16x16x32_bf16 v[98:101], v[172:175], v[176:179], v[98:101]
	ds_read_b128 v[176:179], v0
	v_mfma_f32_16x16x32_bf16 v[158:161], v[172:175], v[198:201], v[158:161]
	ds_read_b128 v[198:201], v163 offset:18432
	v_mfma_f32_16x16x32_bf16 v[154:157], v[172:175], v[202:205], v[154:157]
	ds_read_b128 v[202:205], v163 offset:20480
	v_mfma_f32_16x16x32_bf16 v[150:153], v[172:175], v[206:209], v[150:153]
	ds_read_b128 v[172:175], v163 offset:16384
	ds_read_b128 v[206:209], v163 offset:22528
	s_waitcnt lgkmcnt(1)
	v_mfma_f32_16x16x32_bf16 v[126:129], v[176:179], v[172:175], v[126:129]
	v_mfma_f32_16x16x32_bf16 v[146:149], v[176:179], v[198:201], v[146:149]
	v_mfma_f32_16x16x32_bf16 v[142:145], v[176:179], v[202:205], v[142:145]
	s_waitcnt lgkmcnt(0)
	v_mfma_f32_16x16x32_bf16 v[138:141], v[176:179], v[206:209], v[138:141]
	ds_read_b128 v[176:179], v0 offset:2048
	s_waitcnt lgkmcnt(0)
	v_mfma_f32_16x16x32_bf16 v[118:121], v[176:179], v[172:175], v[118:121]
	v_mfma_f32_16x16x32_bf16 v[102:105], v[176:179], v[198:201], v[102:105]
	v_mfma_f32_16x16x32_bf16 v[106:109], v[176:179], v[202:205], v[106:109]
	v_mfma_f32_16x16x32_bf16 v[114:117], v[176:179], v[206:209], v[114:117]
	ds_read_b128 v[176:179], v0 offset:4096
	s_waitcnt lgkmcnt(0)
	v_mfma_f32_16x16x32_bf16 v[110:113], v[176:179], v[172:175], v[110:113]
	v_mfma_f32_16x16x32_bf16 v[122:125], v[176:179], v[198:201], v[122:125]
	v_mfma_f32_16x16x32_bf16 v[134:137], v[176:179], v[202:205], v[134:137]
	v_mfma_f32_16x16x32_bf16 v[130:133], v[176:179], v[206:209], v[130:133]
	ds_read_b128 v[176:179], v0 offset:6144
	s_waitcnt vmcnt(15)
	ds_write_b128 v167, v[66:69] offset:32768
	s_waitcnt vmcnt(14)
	ds_write_b128 v167, v[70:73] offset:49152
	s_waitcnt vmcnt(13)
	ds_write_b128 v167, v[74:77] offset:36864
	s_waitcnt vmcnt(12)
	ds_write_b128 v167, v[78:81] offset:53248
	s_waitcnt vmcnt(11)
	ds_write_b128 v167, v[82:85] offset:40960
	s_waitcnt vmcnt(10)
	ds_write_b128 v167, v[86:89] offset:57344
	s_waitcnt vmcnt(9)
	ds_write_b128 v167, v[90:93] offset:45056
	s_waitcnt vmcnt(8)
	ds_write_b128 v167, v[94:97] offset:61440
	s_waitcnt lgkmcnt(0)
	s_barrier
	ds_read_b128 v[66:69], v165 offset:32768
	ds_read_b128 v[74:77], v170 offset:49152
	s_waitcnt lgkmcnt(0)
	v_mfma_f32_16x16x32_bf16 v[78:81], v[66:69], v[74:77], v[126:129]
	ds_read_b128 v[82:85], v170 offset:51200
	ds_read_b128 v[90:93], v170 offset:53248
	s_nop 0
	ds_read_b128 v[126:129], v170 offset:55296
	s_waitcnt lgkmcnt(2)
	v_mfma_f32_16x16x32_bf16 v[86:89], v[66:69], v[82:85], v[146:149]
	ds_read_b128 v[168:171], v163 offset:51200
	s_waitcnt lgkmcnt(2)
	v_mfma_f32_16x16x32_bf16 v[94:97], v[66:69], v[90:93], v[142:145]
	s_waitcnt lgkmcnt(1)
	v_mfma_f32_16x16x32_bf16 v[66:69], v[66:69], v[126:129], v[138:141]
	s_nop 2
	ds_read_b128 v[138:141], v165 offset:34816
	s_waitcnt lgkmcnt(0)
	v_mfma_f32_16x16x32_bf16 v[142:145], v[138:141], v[90:93], v[106:109]
	s_nop 2
	ds_read_b128 v[106:109], v165 offset:36864
	v_mfma_f32_16x16x32_bf16 v[118:121], v[138:141], v[74:77], v[118:121]
	v_mfma_f32_16x16x32_bf16 v[102:105], v[138:141], v[82:85], v[102:105]
	v_mfma_f32_16x16x32_bf16 v[114:117], v[138:141], v[126:129], v[114:117]
	s_waitcnt lgkmcnt(0)
	v_mfma_f32_16x16x32_bf16 v[138:141], v[106:109], v[74:77], v[110:113]
	v_mfma_f32_16x16x32_bf16 v[146:149], v[106:109], v[82:85], v[122:125]
	v_mfma_f32_16x16x32_bf16 v[134:137], v[106:109], v[90:93], v[134:137]
	v_mfma_f32_16x16x32_bf16 v[130:133], v[106:109], v[126:129], v[130:133]
	ds_read_b128 v[106:109], v165 offset:38912
	v_mfma_f32_16x16x32_bf16 v[98:101], v[176:179], v[172:175], v[98:101]
	ds_read_b128 v[172:175], v163 offset:53248
	v_mfma_f32_16x16x32_bf16 v[158:161], v[176:179], v[198:201], v[158:161]
	s_waitcnt lgkmcnt(1)
	v_mfma_f32_16x16x32_bf16 v[98:101], v[106:109], v[74:77], v[98:101]
	ds_read_b128 v[74:77], v0 offset:32768
	v_mfma_f32_16x16x32_bf16 v[154:157], v[176:179], v[202:205], v[154:157]
	v_mfma_f32_16x16x32_bf16 v[70:73], v[176:179], v[206:209], v[150:153]
	ds_read_b128 v[176:179], v163 offset:55296
	v_mfma_f32_16x16x32_bf16 v[82:85], v[106:109], v[82:85], v[158:161]
	s_nop 2
	ds_read_b128 v[158:161], v163 offset:49152
	v_mfma_f32_16x16x32_bf16 v[150:153], v[106:109], v[90:93], v[154:157]
	v_mfma_f32_16x16x32_bf16 v[154:157], v[106:109], v[126:129], v[70:73]
	s_waitcnt lgkmcnt(0)
	v_mfma_f32_16x16x32_bf16 v[126:129], v[74:77], v[158:161], v[78:81]
	v_mfma_f32_16x16x32_bf16 v[78:81], v[74:77], v[176:179], v[66:69]
	s_nop 2
	ds_read_b128 v[66:69], v0 offset:34816
	v_mfma_f32_16x16x32_bf16 v[110:113], v[74:77], v[168:171], v[86:89]
	v_mfma_f32_16x16x32_bf16 v[94:97], v[74:77], v[172:175], v[94:97]
	s_waitcnt lgkmcnt(0)
	v_mfma_f32_16x16x32_bf16 v[122:125], v[66:69], v[158:161], v[118:121]
	v_mfma_f32_16x16x32_bf16 v[106:109], v[66:69], v[168:171], v[102:105]
	v_mfma_f32_16x16x32_bf16 v[90:93], v[66:69], v[172:175], v[142:145]
	v_mfma_f32_16x16x32_bf16 v[74:77], v[66:69], v[176:179], v[114:117]
	ds_read_b128 v[66:69], v0 offset:36864
	s_waitcnt lgkmcnt(0)
	v_mfma_f32_16x16x32_bf16 v[118:121], v[66:69], v[158:161], v[138:141]
	v_mfma_f32_16x16x32_bf16 v[102:105], v[66:69], v[168:171], v[146:149]
	v_mfma_f32_16x16x32_bf16 v[86:89], v[66:69], v[172:175], v[134:137]
	s_nop 1
	v_mov_b32_e32 v146, v180
	v_mfma_f32_16x16x32_bf16 v[70:73], v[66:69], v[176:179], v[130:133]
	ds_read_b128 v[66:69], v0 offset:38912
	s_waitcnt lgkmcnt(0)
	s_barrier
	v_mfma_f32_16x16x32_bf16 v[114:117], v[66:69], v[158:161], v[98:101]
	v_mfma_f32_16x16x32_bf16 v[98:101], v[66:69], v[168:171], v[82:85]
	v_mfma_f32_16x16x32_bf16 v[82:85], v[66:69], v[172:175], v[150:153]
	v_mfma_f32_16x16x32_bf16 v[66:69], v[66:69], v[176:179], v[154:157]
	s_cbranch_vccnz .LBB0_262
	s_cmp_lt_u32 s20, 18
	s_cbranch_scc1 .LBB0_263
	s_cmp_eq_u32 s20, 18
	s_cbranch_scc1 .LBB0_264
	s_cmp_lt_u32 s20, 27
	s_mov_b64 s[6:7], 0
	s_cbranch_scc1 .LBB0_856
	s_cmp_lt_u32 s20, 35
	s_mov_b64 s[8:9], 0
	s_cbranch_scc1 .LBB0_857
	s_cmp_lt_u32 s20, 43
	s_mov_b64 s[10:11], 0
	s_cbranch_scc1 .LBB0_862
	s_cmp_lt_u32 s20, 51
	s_cbranch_scc1 .LBB0_865
	s_cmp_lt_u32 s20, 59
	s_mov_b64 s[42:43], 0
	s_cbranch_scc1 .LBB0_866
	s_cmpk_lt_u32 s20, 0x43
	s_mov_b64 s[46:47], 0
	s_cbranch_scc1 .LBB0_867
	s_cmpk_lt_u32 s20, 0x4b
	s_cselect_b64 s[72:73], -1, 0
	s_cmpk_gt_u32 s20, 0x4a
	s_cselect_b64 s[34:35], -1, 0
	s_and_b64 s[28:29], s[72:73], exec
	s_movk_i32 s28, 0xffbd
	s_cselect_b32 s38, s28, 0xffffffb5
	s_movk_i32 s28, 0x1900
	s_cselect_b32 s28, s28, 0x1d00
	s_branch .LBB0_864

	.amdhsa_kernel _Z9mega_coop6Params
		.amdhsa_group_segment_fixed_size 65536
		.amdhsa_private_segment_fixed_size 0
		.amdhsa_kernarg_size 472
		.amdhsa_user_sgpr_count 2
		.amdhsa_user_sgpr_dispatch_ptr 0
		.amdhsa_user_sgpr_queue_ptr 0
		.amdhsa_user_sgpr_kernarg_segment_ptr 1
		.amdhsa_user_sgpr_dispatch_id 0
		.amdhsa_user_sgpr_kernarg_preload_length 0
		.amdhsa_user_sgpr_kernarg_preload_offset 0
		.amdhsa_user_sgpr_private_segment_size 0
		.amdhsa_uses_dynamic_stack 0
		.amdhsa_enable_private_segment 0
		.amdhsa_system_sgpr_workgroup_id_x 1
		.amdhsa_system_sgpr_workgroup_id_y 0
		.amdhsa_system_sgpr_workgroup_id_z 0
		.amdhsa_system_sgpr_workgroup_info 0
		.amdhsa_system_vgpr_workitem_id 2
		.amdhsa_next_free_vgpr 256
		.amdhsa_next_free_sgpr 102
		.amdhsa_accum_offset 256
		.amdhsa_reserve_vcc 1
		.amdhsa_float_round_mode_32 0
		.amdhsa_float_round_mode_16_64 0
		.amdhsa_float_denorm_mode_32 3
		.amdhsa_float_denorm_mode_16_64 3
		.amdhsa_dx10_clamp 1
		.amdhsa_ieee_mode 1
		.amdhsa_fp16_overflow 0
		.amdhsa_tg_split 0
		.amdhsa_exception_fp_ieee_invalid_op 0
		.amdhsa_exception_fp_denorm_src 0
		.amdhsa_exception_fp_ieee_div_zero 0
		.amdhsa_exception_fp_ieee_overflow 0
		.amdhsa_exception_fp_ieee_underflow 0
		.amdhsa_exception_fp_ieee_inexact 0
		.amdhsa_exception_int_div_zero 0
	.end_amdhsa_kernel

amdhsa.kernels:
  - .agpr_count:     0
    .args:
      - .offset:         0
        .size:           216
        .value_kind:     by_value
      - .offset:         216
        .size:           4
        .value_kind:     hidden_block_count_x
      - .offset:         220
        .size:           4
        .value_kind:     hidden_block_count_y
      - .offset:         224
        .size:           4
        .value_kind:     hidden_block_count_z
      - .offset:         228
        .size:           2
        .value_kind:     hidden_group_size_x
      - .offset:         230
        .size:           2
        .value_kind:     hidden_group_size_y
      - .offset:         232
        .size:           2
        .value_kind:     hidden_group_size_z
      - .offset:         234
        .size:           2
        .value_kind:     hidden_remainder_x
      - .offset:         236
        .size:           2
        .value_kind:     hidden_remainder_y
      - .offset:         238
        .size:           2
        .value_kind:     hidden_remainder_z
      - .offset:         256
        .size:           8
        .value_kind:     hidden_global_offset_x
      - .offset:         264
        .size:           8
        .value_kind:     hidden_global_offset_y
      - .offset:         272
        .size:           8
        .value_kind:     hidden_global_offset_z
      - .offset:         280
        .size:           2
        .value_kind:     hidden_grid_dims
      - .offset:         304
        .size:           8
        .value_kind:     hidden_multigrid_sync_arg
    .group_segment_fixed_size: 65536
    .kernarg_segment_align: 8
    .kernarg_segment_size: 472
    .language:       OpenCL C
    .language_version:
      - 2
      - 0
    .max_flat_workgroup_size: 256
    .name:           _Z9mega_coop6Params
    .private_segment_fixed_size: 0
    .sgpr_count:     108
    .sgpr_spill_count: 176
    .symbol:         _Z9mega_coop6Params.kd
    .uniform_work_group_size: 1
    .uses_dynamic_stack: false
    .vgpr_count:     256
    .vgpr_spill_count: 0
    .wavefront_size: 64
